# barrier arrival by returning atomic: the last arriver of a team barrier / the last XCD leader of a grid barrier sees completion from its own atomic and skips the poll round trip
# speedup vs baseline: 1.0054x; 1.0054x over previous
.Ltb_nowb:
	v_mov_b32_e32 v3, 1
	s_nop 0
	global_atomic_add v4, v129, v3, s[12:13] sc0
	s_mov_b32 s21, 0
	s_waitcnt vmcnt(0)
	v_readfirstlane_b32 s20, v4
	s_add_i32 s20, s20, 1
	s_cmp_ge_u32 s20, s19
	s_cbranch_scc1 .Ltb_done

.LBB0_440:
	v_readlane_b32 s6, v254, 40
	v_readlane_b32 s7, v254, 41
	v_readlane_b32 s12, v254, 44
	v_readlane_b32 s13, v254, 45
	v_mov_b32_e32 v3, 1
	v_cvt_f32_u32_e32 v4, v2
	v_sub_u32_e32 v6, 0, v2
	s_nop 1
	global_atomic_add v5, v129, v3, s[6:7] sc0
	v_rcp_iflag_f32_e32 v4, v4
	s_waitcnt lgkmcnt(0)
	v_readfirstlane_b32 s14, v2
	v_readfirstlane_b32 s15, v0
	v_mul_f32_e32 v4, 0x4f7ffffe, v4
	v_cvt_u32_f32_e32 v4, v4
	v_mul_lo_u32 v1, v6, v4
	v_mul_hi_u32 v1, v4, v1
	v_add_u32_e32 v1, v4, v1
	s_waitcnt vmcnt(0)
	v_mul_hi_u32 v1, v5, v1
	v_mul_lo_u32 v6, v1, v2
	v_sub_u32_e32 v6, v5, v6
	v_add_u32_e32 v4, 1, v1
	v_cmp_ge_u32_e32 vcc, v6, v2
	s_nop 1
	v_cndmask_b32_e32 v1, v1, v4, vcc
	v_sub_u32_e32 v4, v6, v2
	v_cndmask_b32_e32 v6, v6, v4, vcc
	v_add_u32_e32 v4, 1, v1
	v_cmp_ge_u32_e32 vcc, v6, v2
	s_nop 1
	v_cndmask_b32_e32 v1, v1, v4, vcc
	v_readfirstlane_b32 s16, v1
	v_readfirstlane_b32 s17, v5
	s_add_i32 s19, s16, 1
	s_mul_i32 s20, s19, s14
	s_add_i32 s17, s17, 1
	s_mul_i32 s19, s19, s15
	s_cmp_lg_u32 s17, s20
	s_cbranch_scc1 .Lxb_poll
	buffer_wbl2 sc1
	s_waitcnt vmcnt(0)
	global_atomic_add v4, v129, v3, s[12:13] sc0
	s_waitcnt vmcnt(0)
	v_readfirstlane_b32 s20, v4
	s_add_i32 s20, s20, 1
	s_sub_i32 s20, s20, s19
	s_cmp_ge_i32 s20, 0
	s_cbranch_scc1 .Lxb_done
